# LN loops: row prefetch two rows ahead (two landing buffers, parity select)
# baseline (speedup 1.0000x reference)
; __device__ __forceinline__ float bflo(unsigned w) { return __uint_as_float(w << 16); }
; __device__ __forceinline__ float bfhi(unsigned w) { return __uint_as_float(w & 0xffff0000u); }
; __device__ __forceinline__ void ln_rows(const bf16* Yb, const float* g, const float* bt, float* outf, bf16* outb, int gw, int NGW, int lane) {
;     u32x4 nx[4];
;     if (gw < M) { const u32x4* yr = (const u32x4*)(Yb + (size_t)gw * D) + lane;
; #pragma unroll
;         for (int j = 0; j < 4; ++j) nx[j] = yr[64 * j]; }
;     for (int row = gw; row < M; row += NGW) {
;         float v[4][8]; float s = 0.f;
; #pragma unroll
;         for (int j = 0; j < 4; ++j) { const u32x4 w = nx[j]; v[j][0] = bflo(w.x); v[j][1] = bfhi(w.x); v[j][2] = bflo(w.y); v[j][3] = bfhi(w.y); v[j][4] = bflo(w.z); v[j][5] = bfhi(w.z); v[j][6] = bflo(w.w); v[j][7] = bfhi(w.w);
;             s += ((v[j][0] + v[j][1]) + (v[j][2] + v[j][3])) + ((v[j][4] + v[j][5]) + (v[j][6] + v[j][7])); }
;         if (row + NGW < M) { const u32x4* yr = (const u32x4*)(Yb + (size_t)(row + NGW) * D) + lane;
; #pragma unroll
;             for (int j = 0; j < 4; ++j) nx[j] = yr[64 * j]; }
.LBB0_454:
	s_cmp_lt_i32 s44, 5
	s_cselect_b64 s[6:7], -1, 0
	s_and_b64 s[6:7], s[6:7], s[4:5]
	s_cmp_lt_i32 s38, 0x8000
	s_cselect_b64 s[10:11], -1, 0
	s_and_b64 s[4:5], s[6:7], s[10:11]
	s_andn2_b64 vcc, exec, s[4:5]
	v_lshlrev_b32_e32 v136, 4, v171
	v_mbcnt_lo_u32_b32 v172, -1, 0
	v_lshlrev_b32_e32 v138, 5, v171
	s_cbranch_vccnz .LBB0_459
	s_ashr_i32 s39, s38, 31
	s_lshl_b64 s[4:5], s[38:39], 12
	s_waitcnt lgkmcnt(0)
	s_add_u32 s12, s8, s4
	s_addc_u32 s13, s9, s5
	global_load_dwordx4 v[28:31], v136, s[12:13]
	global_load_dwordx4 v[24:27], v136, s[12:13] offset:1024
	global_load_dwordx4 v[20:23], v136, s[12:13] offset:2048
	global_load_dwordx4 v[16:19], v136, s[12:13] offset:3072
	v_mbcnt_hi_u32_b32 v0, -1, v172
	v_and_b32_e32 v1, 64, v0
	v_add_u32_e32 v1, 64, v1
	v_xor_b32_e32 v2, 1, v0
	v_cmp_lt_i32_e32 vcc, v2, v1
	s_load_dwordx4 s[12:15], s[0:1], 0x88
	v_mov_b32_e32 v137, 0
	v_cndmask_b32_e32 v2, v0, v2, vcc
	v_lshlrev_b32_e32 v53, 2, v2
	v_xor_b32_e32 v2, 2, v0
	v_cmp_lt_i32_e32 vcc, v2, v1
	v_mov_b32_e32 v139, v137
	s_waitcnt lgkmcnt(0)
	v_lshl_add_u64 v[32:33], s[12:13], 0, v[138:139]
	v_cndmask_b32_e32 v2, v0, v2, vcc
	v_lshlrev_b32_e32 v54, 2, v2
	v_xor_b32_e32 v2, 4, v0
	v_cmp_lt_i32_e32 vcc, v2, v1
	v_lshl_add_u64 v[34:35], s[14:15], 0, v[138:139]
	s_movk_i32 s3, 0x7fff
	v_cndmask_b32_e32 v2, v0, v2, vcc
	v_lshlrev_b32_e32 v55, 2, v2
	v_xor_b32_e32 v2, 8, v0
	v_cmp_lt_i32_e32 vcc, v2, v1
	s_mov_b32 s20, 0xffff0000
	v_mov_b32_e32 v59, 0x3727c5ac
	v_cndmask_b32_e32 v2, v0, v2, vcc
	v_lshlrev_b32_e32 v56, 2, v2
	v_xor_b32_e32 v2, 16, v0
	v_cmp_lt_i32_e32 vcc, v2, v1
	s_mov_b32 s21, 0xf800000
	v_mov_b32_e32 v60, 0x260
	v_cndmask_b32_e32 v2, v0, v2, vcc
	v_lshlrev_b32_e32 v57, 2, v2
	v_xor_b32_e32 v2, 32, v0
	v_cmp_lt_i32_e32 vcc, v2, v1
	v_mov_b32_e32 v1, v137
	s_mov_b32 s22, 0x25800000
	v_cndmask_b32_e32 v0, v0, v2, vcc
	v_lshlrev_b32_e32 v58, 2, v0
	v_or_b32_e32 v0, 0x1000, v138
	v_lshl_add_u64 v[36:37], s[12:13], 0, v[0:1]
	v_lshl_add_u64 v[38:39], s[14:15], 0, v[0:1]
	v_or_b32_e32 v0, 0x1800, v138
	v_lshl_add_u64 v[40:41], s[12:13], 0, v[0:1]
	s_add_u32 s12, s42, s4
	s_addc_u32 s13, s43, s5
	s_add_i32 s4, s38, s56
	s_ashr_i32 s57, s56, 31
	s_ashr_i32 s5, s4, 31
	v_lshl_add_u64 v[42:43], s[14:15], 0, v[0:1]
	s_lshl_b64 s[14:15], s[56:57], 12
	s_lshl_b64 s[4:5], s[4:5], 12
	s_add_u32 s16, s42, s4
	s_addc_u32 s17, s43, s5
	s_mov_b32 s23, s38
	global_load_dwordx4 v[176:179], v[32:33], off
	global_load_dwordx4 v[184:187], v[34:35], off
	global_load_dwordx4 v[180:183], v[32:33], off offset:16
	global_load_dwordx4 v[188:191], v[34:35], off offset:16
	global_load_dwordx4 v[192:195], v[32:33], off offset:2048
	global_load_dwordx4 v[200:203], v[34:35], off offset:2048
	global_load_dwordx4 v[196:199], v[32:33], off offset:2064
	global_load_dwordx4 v[204:207], v[34:35], off offset:2064
	global_load_dwordx4 v[208:211], v[36:37], off
	global_load_dwordx4 v[216:219], v[38:39], off
	global_load_dwordx4 v[212:215], v[36:37], off offset:16
	global_load_dwordx4 v[220:223], v[38:39], off offset:16
	global_load_dwordx4 v[224:227], v[40:41], off
	global_load_dwordx4 v[232:235], v[42:43], off
	global_load_dwordx4 v[228:231], v[40:41], off offset:16
	global_load_dwordx4 v[236:239], v[42:43], off offset:16
	s_mov_b32 s98, 0
	s_add_i32 s99, s38, s56
	s_cmpk_gt_i32 s99, 0x7fff
	s_cbranch_scc1 .Lln1_pre_done
	v_lshl_add_u64 v[124:125], s[16:17], 0, v[136:137]
	v_add_co_u32_e32 v124, vcc, 0x35800000, v124
	s_nop 1
	v_addc_co_u32_e32 v125, vcc, 0, v125, vcc
	global_load_dwordx4 v[4:7], v[124:125], off
	global_load_dwordx4 v[8:11], v[124:125], off offset:1024
	global_load_dwordx4 v[12:15], v[124:125], off offset:2048
	global_load_dwordx4 v[0:3], v[124:125], off offset:3072
	s_add_u32 s16, s16, s14
	s_addc_u32 s17, s17, s15
.Lln1_pre_done:
	s_waitcnt vmcnt(0)
	s_branch .LBB0_457
.LBB0_456:
	v_lshlrev_b32_e32 v46, 16, v30
	v_and_b32_e32 v47, 0xffff0000, v30
	v_lshlrev_b32_e32 v30, 16, v31
	v_and_b32_e32 v31, 0xffff0000, v31
	v_lshlrev_b32_e32 v44, 16, v28
	v_and_b32_e32 v45, 0xffff0000, v28
	v_lshlrev_b32_e32 v28, 16, v29
	v_and_b32_e32 v29, 0xffff0000, v29
	v_add_f32_e32 v48, v31, v30
	v_add_f32_e32 v49, v47, v46
	v_add_f32_e32 v48, v49, v48
	v_add_f32_e32 v49, v29, v28
	v_add_f32_e32 v50, v45, v44
	v_add_f32_e32 v49, v50, v49
	v_add_f32_e32 v48, v49, v48
	v_lshlrev_b32_e32 v50, 16, v26
	v_and_b32_e32 v51, 0xffff0000, v26
	v_lshlrev_b32_e32 v26, 16, v27
	v_and_b32_e32 v27, 0xffff0000, v27
	v_add_f32_e32 v52, 0, v48
	v_lshlrev_b32_e32 v48, 16, v24
	v_and_b32_e32 v49, 0xffff0000, v24
	v_lshlrev_b32_e32 v24, 16, v25
	v_and_b32_e32 v25, 0xffff0000, v25
	v_add_f32_e32 v61, v27, v26
	v_add_f32_e32 v62, v51, v50
	v_add_f32_e32 v61, v62, v61
	v_add_f32_e32 v62, v25, v24
	v_add_f32_e32 v63, v49, v48
	v_add_f32_e32 v62, v63, v62
	v_add_f32_e32 v61, v62, v61
	v_lshlrev_b32_e32 v64, 16, v22
	v_and_b32_e32 v65, 0xffff0000, v22
	v_lshlrev_b32_e32 v22, 16, v23
	v_and_b32_e32 v23, 0xffff0000, v23
	v_add_f32_e32 v52, v61, v52
	v_lshlrev_b32_e32 v62, 16, v20
	v_and_b32_e32 v63, 0xffff0000, v20
	v_lshlrev_b32_e32 v20, 16, v21
	v_and_b32_e32 v21, 0xffff0000, v21
	v_add_f32_e32 v61, v23, v22
	v_add_f32_e32 v66, v65, v64
	v_add_f32_e32 v61, v66, v61
	v_add_f32_e32 v66, v21, v20
	v_add_f32_e32 v67, v63, v62
	v_add_f32_e32 v66, v67, v66
	v_add_f32_e32 v61, v66, v61
	v_lshlrev_b32_e32 v68, 16, v18
	v_and_b32_e32 v69, 0xffff0000, v18
	v_and_b32_e32 v18, 0xffff0000, v19
	v_lshlrev_b32_e32 v19, 16, v19
	v_add_f32_e32 v52, v61, v52
	v_lshlrev_b32_e32 v66, 16, v16
	v_and_b32_e32 v67, 0xffff0000, v16
	v_lshlrev_b32_e32 v16, 16, v17
	v_and_b32_e32 v17, 0xffff0000, v17
	v_add_f32_e32 v61, v19, v18
	v_add_f32_e32 v70, v69, v68
	v_add_f32_e32 v61, v70, v61
	v_add_f32_e32 v70, v17, v16
	v_add_f32_e32 v71, v67, v66
	v_add_f32_e32 v70, v71, v70
	v_add_f32_e32 v61, v70, v61
	v_add_f32_e32 v52, v61, v52
	ds_bpermute_b32 v61, v53, v52
	s_waitcnt lgkmcnt(0)
; __device__ __forceinline__ float wave_sum(float v) {
; #pragma unroll
;     for (int o = 1; o < 64; o <<= 1) v += __shfl_xor(v, o);
;     return v;
; }
; __device__ __forceinline__ void ln_rows(const bf16* Yb, const float* g, const float* bt, float* outf, bf16* outb, int gw, int NGW, int lane) {
;     ...
;         const float mean = wave_sum(s) * (1.f / D); float s2 = 0.f;
; #pragma unroll
;         for (int j = 0; j < 4; ++j)
; #pragma unroll
;             for (int i = 0; i < 8; ++i) { v[j][i] -= mean; s2 += v[j][i] * v[j][i]; }
;         const float rstd = 1.f / sqrtf(wave_sum(s2) * (1.f / D) + LN_EPS);
; #pragma unroll
;         for (int j = 0; j < 4; ++j) { const int col = 8 * (lane + 64 * j);
;             const f32x4 g0 = *(const f32x4*)(g + col), g1 = *(const f32x4*)(g + col + 4), b0 = *(const f32x4*)(bt + col), b1 = *(const f32x4*)(bt + col + 4);
;             const f32x4 o0 = (f32x4){v[j][0], v[j][1], v[j][2], v[j][3]} * rstd * g0 + b0, o1 = (f32x4){v[j][4], v[j][5], v[j][6], v[j][7]} * rstd * g1 + b1;
;             if (outf) { *(f32x4*)(outf + (size_t)row * D + col) = o0; *(f32x4*)(outf + (size_t)row * D + col + 4) = o1; }
	v_add_f32_e32 v52, v52, v61
	ds_bpermute_b32 v61, v54, v52
	s_waitcnt lgkmcnt(0)
	v_add_f32_e32 v52, v52, v61
	ds_bpermute_b32 v61, v55, v52
	s_waitcnt lgkmcnt(0)
	v_add_f32_e32 v52, v52, v61
	ds_bpermute_b32 v61, v56, v52
	s_waitcnt lgkmcnt(0)
	v_add_f32_e32 v52, v52, v61
	ds_bpermute_b32 v61, v57, v52
	s_waitcnt lgkmcnt(0)
	v_add_f32_e32 v52, v52, v61
	ds_bpermute_b32 v61, v58, v52
	s_waitcnt lgkmcnt(0)
	v_add_f32_e32 v52, v52, v61
	v_mul_f32_e32 v52, 0x3a000000, v52
	v_pk_add_f32 v[70:71], v[44:45], v[52:53] op_sel_hi:[1,0] neg_lo:[0,1] neg_hi:[0,1]
	v_pk_add_f32 v[74:75], v[28:29], v[52:53] op_sel_hi:[1,0] neg_lo:[0,1] neg_hi:[0,1]
	v_pk_mul_f32 v[72:73], v[70:71], v[70:71]
	v_pk_mul_f32 v[28:29], v[74:75], v[74:75]
	v_pk_add_f32 v[88:89], v[50:51], v[52:53] op_sel_hi:[1,0] neg_lo:[0,1] neg_hi:[0,1]
	v_pk_add_f32 v[50:51], v[18:19], v[52:53] op_sel_hi:[1,0] neg_lo:[0,1] neg_hi:[0,1]
	v_add_f32_e32 v18, v72, v73
	v_pk_add_f32 v[76:77], v[46:47], v[52:53] op_sel_hi:[1,0] neg_lo:[0,1] neg_hi:[0,1]
	v_add_f32_e32 v18, v28, v18
	v_pk_mul_f32 v[78:79], v[76:77], v[76:77]
	v_add_f32_e32 v18, v29, v18
	v_pk_add_f32 v[80:81], v[30:31], v[52:53] op_sel_hi:[1,0] neg_lo:[0,1] neg_hi:[0,1]
	v_add_f32_e32 v18, v78, v18
	v_pk_mul_f32 v[30:31], v[80:81], v[80:81]
	v_add_f32_e32 v18, v79, v18
	v_pk_add_f32 v[82:83], v[48:49], v[52:53] op_sel_hi:[1,0] neg_lo:[0,1] neg_hi:[0,1]
	v_add_f32_e32 v18, v30, v18
	v_pk_mul_f32 v[84:85], v[82:83], v[82:83]
	v_add_f32_e32 v18, v31, v18
	v_pk_add_f32 v[86:87], v[24:25], v[52:53] op_sel_hi:[1,0] neg_lo:[0,1] neg_hi:[0,1]
	v_add_f32_e32 v18, v84, v18
	v_pk_mul_f32 v[24:25], v[86:87], v[86:87]
	v_add_f32_e32 v18, v85, v18
	v_add_f32_e32 v18, v24, v18
	v_pk_mul_f32 v[90:91], v[88:89], v[88:89]
	v_add_f32_e32 v18, v25, v18
	v_pk_add_f32 v[92:93], v[26:27], v[52:53] op_sel_hi:[1,0] neg_lo:[0,1] neg_hi:[0,1]
	v_add_f32_e32 v18, v90, v18
	v_pk_mul_f32 v[26:27], v[92:93], v[92:93]
	v_add_f32_e32 v18, v91, v18
	v_pk_add_f32 v[62:63], v[62:63], v[52:53] op_sel_hi:[1,0] neg_lo:[0,1] neg_hi:[0,1]
	v_add_f32_e32 v18, v26, v18
	v_pk_mul_f32 v[94:95], v[62:63], v[62:63]
	v_add_f32_e32 v18, v27, v18
	v_pk_add_f32 v[96:97], v[20:21], v[52:53] op_sel_hi:[1,0] neg_lo:[0,1] neg_hi:[0,1]
	v_add_f32_e32 v18, v94, v18
	v_pk_mul_f32 v[20:21], v[96:97], v[96:97]
	v_add_f32_e32 v18, v95, v18
	v_pk_add_f32 v[64:65], v[64:65], v[52:53] op_sel_hi:[1,0] neg_lo:[0,1] neg_hi:[0,1]
	v_add_f32_e32 v18, v20, v18
	v_pk_mul_f32 v[98:99], v[64:65], v[64:65]
	v_add_f32_e32 v18, v21, v18
	v_pk_add_f32 v[100:101], v[22:23], v[52:53] op_sel_hi:[1,0] neg_lo:[0,1] neg_hi:[0,1]
	v_add_f32_e32 v18, v98, v18
	v_pk_mul_f32 v[22:23], v[100:101], v[100:101]
	v_add_f32_e32 v18, v99, v18
	v_pk_add_f32 v[44:45], v[66:67], v[52:53] op_sel_hi:[1,0] neg_lo:[0,1] neg_hi:[0,1]
	v_add_f32_e32 v18, v22, v18
	v_pk_mul_f32 v[66:67], v[44:45], v[44:45]
	v_add_f32_e32 v18, v23, v18
	v_pk_add_f32 v[46:47], v[16:17], v[52:53] op_sel_hi:[1,0] neg_lo:[0,1] neg_hi:[0,1]
	v_add_f32_e32 v18, v66, v18
	v_pk_mul_f32 v[16:17], v[46:47], v[46:47]
	v_add_f32_e32 v18, v67, v18
	v_pk_add_f32 v[48:49], v[68:69], v[52:53] op_sel_hi:[1,0] neg_lo:[0,1] neg_hi:[0,1]
	v_add_f32_e32 v16, v16, v18
	v_pk_mul_f32 v[68:69], v[48:49], v[48:49]
	v_add_f32_e32 v16, v17, v16
	v_add_f32_e32 v16, v68, v16
	v_pk_mul_f32 v[102:103], v[50:51], v[50:51]
	v_add_f32_e32 v24, v69, v16
	v_add_f32_e32 v24, v103, v24
	v_add_f32_e32 v52, v102, v24
	ds_bpermute_b32 v61, v53, v52
	s_waitcnt lgkmcnt(0)
	v_add_f32_e32 v52, v52, v61
	ds_bpermute_b32 v61, v54, v52
	s_waitcnt lgkmcnt(0)
	v_add_f32_e32 v52, v52, v61
	ds_bpermute_b32 v61, v55, v52
	s_waitcnt lgkmcnt(0)
	v_add_f32_e32 v52, v52, v61
	ds_bpermute_b32 v61, v56, v52
	s_waitcnt lgkmcnt(0)
	v_add_f32_e32 v52, v52, v61
	ds_bpermute_b32 v61, v57, v52
	s_waitcnt lgkmcnt(0)
	v_add_f32_e32 v52, v52, v61
	ds_bpermute_b32 v61, v58, v52
	s_waitcnt lgkmcnt(0)
	v_add_f32_e32 v52, v52, v61
	v_fmamk_f32 v52, v52, 0x3a000000, v59
	v_mul_f32_e32 v61, 0x4f800000, v52
	v_cmp_gt_f32_e32 vcc, s21, v52
	s_nop 1
	v_cndmask_b32_e32 v52, v52, v61, vcc
	v_sqrt_f32_e32 v61, v52
	s_nop 0
	v_add_u32_e32 v66, -1, v61
	v_fma_f32 v67, -v66, v61, v52
	v_cmp_ge_f32_e64 s[4:5], 0, v67
	v_add_u32_e32 v67, 1, v61
	s_nop 0
	v_cndmask_b32_e64 v66, v61, v66, s[4:5]
	v_fma_f32 v61, -v67, v61, v52
	v_cmp_lt_f32_e64 s[4:5], 0, v61
	s_nop 1
	v_cndmask_b32_e64 v61, v66, v67, s[4:5]
	v_mul_f32_e32 v66, 0x37800000, v61
	v_cndmask_b32_e32 v61, v61, v66, vcc
	v_cmp_class_f32_e32 vcc, v52, v60
	s_nop 1
	v_cndmask_b32_e32 v52, v61, v52, vcc
	v_div_scale_f32 v61, s[4:5], v52, v52, 1.0
	v_rcp_f32_e32 v66, v61
	s_nop 0
	v_fma_f32 v67, -v61, v66, 1.0
	v_fmac_f32_e32 v66, v67, v66
	v_div_scale_f32 v67, vcc, 1.0, v52, 1.0
	v_mul_f32_e32 v68, v67, v66
	v_fma_f32 v69, -v61, v68, v67
	v_fmac_f32_e32 v68, v69, v66
	v_fma_f32 v61, -v61, v68, v67
	v_div_fmas_f32 v61, v61, v66, v68
	v_div_fixup_f32 v52, v61, v52, 1.0
	v_pk_mul_f32 v[66:67], v[70:71], v[52:53] op_sel_hi:[1,0]
	v_pk_mul_f32 v[68:69], v[74:75], v[52:53] op_sel_hi:[1,0]
	v_pk_fma_f32 v[16:17], v[176:177], v[66:67], v[184:185]
	v_pk_mul_f32 v[20:21], v[76:77], v[52:53] op_sel_hi:[1,0]
	v_pk_fma_f32 v[18:19], v[178:179], v[68:69], v[186:187]
	v_pk_fma_f32 v[20:21], v[180:181], v[20:21], v[188:189]
	v_bfe_u32 v24, v16, 16, 1
	v_add3_u32 v16, v16, v24, s3
	v_bfe_u32 v24, v17, 16, 1
	v_lshrrev_b32_e32 v16, 16, v16
	v_add3_u32 v17, v17, v24, s3
	v_and_or_b32 v16, v17, s20, v16
	v_bfe_u32 v17, v18, 16, 1
	v_add3_u32 v17, v18, v17, s3
	v_bfe_u32 v18, v19, 16, 1
	v_lshrrev_b32_e32 v17, 16, v17
	v_add3_u32 v18, v19, v18, s3
	v_and_or_b32 v17, v18, s20, v17
; __device__ __forceinline__ unsigned pk2(float lo, float hi) { return f2bf(lo) | (f2bf(hi) << 16); }
; __device__ __forceinline__ void ln_rows(const bf16* Yb, const float* g, const float* bt, float* outf, bf16* outb, int gw, int NGW, int lane) {
;     ...
;         if (row + NGW < M) { const u32x4* yr = (const u32x4*)(Yb + (size_t)(row + NGW) * D) + lane;
; #pragma unroll
;             for (int j = 0; j < 4; ++j) nx[j] = yr[64 * j]; }
;     ...
; #pragma unroll
;         for (int j = 0; j < 4; ++j) { const int col = 8 * (lane + 64 * j);
;             const f32x4 g0 = *(const f32x4*)(g + col), g1 = *(const f32x4*)(g + col + 4), b0 = *(const f32x4*)(bt + col), b1 = *(const f32x4*)(bt + col + 4);
;             const f32x4 o0 = (f32x4){v[j][0], v[j][1], v[j][2], v[j][3]} * rstd * g0 + b0, o1 = (f32x4){v[j][4], v[j][5], v[j][6], v[j][7]} * rstd * g1 + b1;
;             if (outf) { *(f32x4*)(outf + (size_t)row * D + col) = o0; *(f32x4*)(outf + (size_t)row * D + col + 4) = o1; }
;             if (outb) { u32x4 w; w.x = pk2(o0[0], o0[1]); w.y = pk2(o0[2], o0[3]); w.z = pk2(o1[0], o1[1]); w.w = pk2(o1[2], o1[3]); *(u32x4*)(outb + (size_t)row * D + col) = w; } }
	v_bfe_u32 v18, v20, 16, 1
	v_pk_mul_f32 v[22:23], v[80:81], v[52:53] op_sel_hi:[1,0]
	v_add3_u32 v18, v20, v18, s3
	v_bfe_u32 v19, v21, 16, 1
	v_pk_fma_f32 v[22:23], v[182:183], v[22:23], v[190:191]
	v_lshrrev_b32_e32 v18, 16, v18
	v_add3_u32 v19, v21, v19, s3
	v_and_or_b32 v18, v19, s20, v18
	v_bfe_u32 v19, v22, 16, 1
	v_add3_u32 v19, v22, v19, s3
	v_bfe_u32 v20, v23, 16, 1
	v_lshrrev_b32_e32 v19, 16, v19
	v_add3_u32 v20, v23, v20, s3
	v_and_or_b32 v19, v20, s20, v19
	v_lshl_add_u64 v[20:21], s[12:13], 0, v[136:137]
	v_add_co_u32_e32 v78, vcc, s22, v20
	v_pk_mul_f32 v[66:67], v[82:83], v[52:53] op_sel_hi:[1,0]
	s_nop 0
	v_addc_co_u32_e32 v79, vcc, 0, v21, vcc
	global_store_dwordx4 v[78:79], v[16:19], off
	v_pk_mul_f32 v[68:69], v[86:87], v[52:53] op_sel_hi:[1,0]
	v_pk_mul_f32 v[62:63], v[62:63], v[52:53] op_sel_hi:[1,0]
	v_pk_mul_f32 v[64:65], v[64:65], v[52:53] op_sel_hi:[1,0]
	s_add_u32 s12, s12, s14
	s_addc_u32 s13, s13, s15
	s_add_u32 s16, s16, s14
	s_addc_u32 s17, s17, s15
	s_andn2_b64 vcc, exec, s[18:19]
	v_pk_fma_f32 v[16:17], v[192:193], v[66:67], v[200:201]
	v_pk_mul_f32 v[20:21], v[88:89], v[52:53] op_sel_hi:[1,0]
	v_pk_fma_f32 v[18:19], v[194:195], v[68:69], v[202:203]
	v_pk_fma_f32 v[20:21], v[196:197], v[20:21], v[204:205]
	v_bfe_u32 v24, v16, 16, 1
	v_add3_u32 v16, v16, v24, s3
	v_bfe_u32 v24, v17, 16, 1
	v_lshrrev_b32_e32 v16, 16, v16
	v_add3_u32 v17, v17, v24, s3
	v_and_or_b32 v16, v17, s20, v16
	v_bfe_u32 v17, v18, 16, 1
	v_add3_u32 v17, v18, v17, s3
	v_bfe_u32 v18, v19, 16, 1
	v_lshrrev_b32_e32 v17, 16, v17
	v_add3_u32 v18, v19, v18, s3
	v_and_or_b32 v17, v18, s20, v17
	v_bfe_u32 v18, v20, 16, 1
	v_pk_mul_f32 v[22:23], v[92:93], v[52:53] op_sel_hi:[1,0]
	v_add3_u32 v18, v20, v18, s3
	v_bfe_u32 v19, v21, 16, 1
	v_pk_fma_f32 v[22:23], v[198:199], v[22:23], v[206:207]
	v_lshrrev_b32_e32 v18, 16, v18
	v_add3_u32 v19, v21, v19, s3
	v_and_or_b32 v18, v19, s20, v18
	v_bfe_u32 v19, v22, 16, 1
	v_add3_u32 v19, v22, v19, s3
	v_bfe_u32 v20, v23, 16, 1
	v_lshrrev_b32_e32 v19, 16, v19
	v_add3_u32 v20, v23, v20, s3
	v_and_or_b32 v19, v20, s20, v19
	global_store_dwordx4 v[78:79], v[16:19], off offset:1024
	v_pk_mul_f32 v[66:67], v[96:97], v[52:53] op_sel_hi:[1,0]
	v_pk_mul_f32 v[68:69], v[100:101], v[52:53] op_sel_hi:[1,0]
	s_nop 0
	v_pk_fma_f32 v[18:19], v[210:211], v[66:67], v[218:219]
	v_pk_fma_f32 v[16:17], v[208:209], v[62:63], v[216:217]
	v_pk_fma_f32 v[20:21], v[214:215], v[68:69], v[222:223]
	v_pk_fma_f32 v[22:23], v[212:213], v[64:65], v[220:221]
	v_bfe_u32 v24, v16, 16, 1
	v_bfe_u32 v26, v18, 16, 1
	v_bfe_u32 v28, v22, 16, 1
	v_bfe_u32 v30, v20, 16, 1
	v_bfe_u32 v25, v17, 16, 1
	v_bfe_u32 v27, v19, 16, 1
	v_bfe_u32 v29, v23, 16, 1
	v_bfe_u32 v31, v21, 16, 1
	v_add3_u32 v16, v16, v24, s3
	v_add3_u32 v18, v18, v26, s3
	v_add3_u32 v22, v22, v28, s3
	v_add3_u32 v20, v20, v30, s3
	v_add3_u32 v17, v17, v25, s3
	v_add3_u32 v19, v19, v27, s3
	v_add3_u32 v23, v23, v29, s3
	v_add3_u32 v21, v21, v31, s3
	v_lshrrev_b32_e32 v16, 16, v16
	v_lshrrev_b32_e32 v18, 16, v18
	v_lshrrev_b32_e32 v22, 16, v22
	v_lshrrev_b32_e32 v20, 16, v20
	v_and_or_b32 v16, v17, s20, v16
	v_and_or_b32 v17, v19, s20, v18
	v_and_or_b32 v18, v23, s20, v22
	v_and_or_b32 v19, v21, s20, v20
	global_store_dwordx4 v[78:79], v[16:19], off offset:2048
	s_waitcnt vmcnt(7)
	s_cmp_eq_u32 s98, 0
	s_cbranch_scc1 .Lln1_cpN2
	v_mov_b32_e32 v28, v4
	v_mov_b32_e32 v29, v5
	v_mov_b32_e32 v30, v6
	v_mov_b32_e32 v31, v7
	v_mov_b32_e32 v24, v8
	v_mov_b32_e32 v25, v9
	v_mov_b32_e32 v26, v10
	v_mov_b32_e32 v27, v11
	v_mov_b32_e32 v20, v12
	v_mov_b32_e32 v21, v13
	v_mov_b32_e32 v22, v14
	v_mov_b32_e32 v23, v15
	v_mov_b32_e32 v16, v0
	v_mov_b32_e32 v17, v1
	v_mov_b32_e32 v18, v2
	v_mov_b32_e32 v19, v3
	s_branch .Lln1_cpdone
.Lln1_cpN2:
	v_mov_b32_e32 v28, v108
	v_mov_b32_e32 v29, v109
	v_mov_b32_e32 v30, v110
	v_mov_b32_e32 v31, v111
	v_mov_b32_e32 v24, v112
	v_mov_b32_e32 v25, v113
	v_mov_b32_e32 v26, v114
	v_mov_b32_e32 v27, v115
	v_mov_b32_e32 v20, v116
	v_mov_b32_e32 v21, v117
	v_mov_b32_e32 v22, v118
	v_mov_b32_e32 v23, v119
	v_mov_b32_e32 v16, v120
	v_mov_b32_e32 v17, v121
	v_mov_b32_e32 v18, v122
	v_mov_b32_e32 v19, v123
.Lln1_cpdone:
	v_pk_mul_f32 v[140:141], v[44:45], v[52:53] op_sel_hi:[1,0]
	v_pk_mul_f32 v[144:145], v[46:47], v[52:53] op_sel_hi:[1,0]
	v_pk_mul_f32 v[146:147], v[48:49], v[52:53] op_sel_hi:[1,0]
	v_pk_mul_f32 v[148:149], v[50:51], v[52:53] op_sel:[1,0] op_sel_hi:[0,0]
	v_pk_fma_f32 v[144:145], v[226:227], v[144:145], v[234:235]
	v_pk_fma_f32 v[140:141], v[224:225], v[140:141], v[232:233]
	v_pk_fma_f32 v[148:149], v[230:231], v[148:149], v[238:239]
	v_pk_fma_f32 v[146:147], v[228:229], v[146:147], v[236:237]
	v_bfe_u32 v142, v140, 16, 1
	v_bfe_u32 v151, v144, 16, 1
	v_bfe_u32 v153, v146, 16, 1
	v_bfe_u32 v154, v147, 16, 1
	v_bfe_u32 v155, v148, 16, 1
	v_bfe_u32 v150, v141, 16, 1
	v_bfe_u32 v152, v145, 16, 1
	v_bfe_u32 v156, v149, 16, 1
	v_add3_u32 v140, v140, v142, s3
	v_add3_u32 v142, v144, v151, s3
	v_add3_u32 v144, v146, v153, s3
	v_add3_u32 v146, v147, v154, s3
	v_add3_u32 v147, v148, v155, s3
	v_add3_u32 v141, v141, v150, s3
	v_add3_u32 v145, v145, v152, s3
	v_add3_u32 v148, v149, v156, s3
	v_lshrrev_b32_e32 v140, 16, v140
	v_lshrrev_b32_e32 v142, 16, v142
	v_lshrrev_b32_e32 v149, 16, v144
	v_lshrrev_b32_e32 v147, 16, v147
	v_and_or_b32 v144, v141, s20, v140
	v_and_or_b32 v145, v145, s20, v142
	v_and_or_b32 v146, v146, s20, v149
	v_and_or_b32 v147, v148, s20, v147
	global_store_dwordx4 v[78:79], v[144:147], off offset:3072
	s_cbranch_vccz .LBB0_459
.LBB0_457:
	s_add_i32 s23, s23, s56
	s_cmpk_gt_i32 s23, 0x7fff
	s_cselect_b64 s[18:19], -1, 0
	s_xor_b32 s98, s98, 1
	s_add_i32 s99, s23, s56
	s_cmpk_gt_i32 s99, 0x7fff
	s_cbranch_scc1 .LBB0_456
	v_lshl_add_u64 v[124:125], s[16:17], 0, v[136:137]
	v_add_co_u32_e32 v124, vcc, 0x35800000, v124
	s_nop 1
	v_addc_co_u32_e32 v125, vcc, 0, v125, vcc
	s_cmp_eq_u32 s98, 0
	s_cbranch_scc1 .Lln1_pfN1
	global_load_dwordx4 v[108:111], v[124:125], off
	global_load_dwordx4 v[112:115], v[124:125], off offset:1024
	global_load_dwordx4 v[116:119], v[124:125], off offset:2048
	global_load_dwordx4 v[120:123], v[124:125], off offset:3072
	s_branch .LBB0_456
.Lln1_pfN1:
	global_load_dwordx4 v[4:7], v[124:125], off
	global_load_dwordx4 v[8:11], v[124:125], off offset:1024
	global_load_dwordx4 v[12:15], v[124:125], off offset:2048
	global_load_dwordx4 v[0:3], v[124:125], off offset:3072
	s_branch .LBB0_456

; __device__ __forceinline__ float bflo(unsigned w) { return __uint_as_float(w << 16); }
; __device__ __forceinline__ float bfhi(unsigned w) { return __uint_as_float(w & 0xffff0000u); }
; __device__ __forceinline__ void ln_rows(const bf16* Yb, const float* g, const float* bt, float* outf, bf16* outb, int gw, int NGW, int lane) {
;     u32x4 nx[4];
;     if (gw < M) { const u32x4* yr = (const u32x4*)(Yb + (size_t)gw * D) + lane;
; #pragma unroll
;         for (int j = 0; j < 4; ++j) nx[j] = yr[64 * j]; }
;     for (int row = gw; row < M; row += NGW) {
;         float v[4][8]; float s = 0.f;
; #pragma unroll
;         for (int j = 0; j < 4; ++j) { const u32x4 w = nx[j]; v[j][0] = bflo(w.x); v[j][1] = bfhi(w.x); v[j][2] = bflo(w.y); v[j][3] = bfhi(w.y); v[j][4] = bflo(w.z); v[j][5] = bfhi(w.z); v[j][6] = bflo(w.w); v[j][7] = bfhi(w.w);
;             s += ((v[j][0] + v[j][1]) + (v[j][2] + v[j][3])) + ((v[j][4] + v[j][5]) + (v[j][6] + v[j][7])); }
;         if (row + NGW < M) { const u32x4* yr = (const u32x4*)(Yb + (size_t)(row + NGW) * D) + lane;
; #pragma unroll
;             for (int j = 0; j < 4; ++j) nx[j] = yr[64 * j]; }
;         const float mean = wave_sum(s) * (1.f / D); float s2 = 0.f;
; #pragma unroll
;         for (int j = 0; j < 4; ++j)
; #pragma unroll
;             for (int i = 0; i < 8; ++i) { v[j][i] -= mean; s2 += v[j][i] * v[j][i]; }
;         const float rstd = 1.f / sqrtf(wave_sum(s2) * (1.f / D) + LN_EPS);
; #pragma unroll
;         for (int j = 0; j < 4; ++j) { const int col = 8 * (lane + 64 * j);
;             const f32x4 g0 = *(const f32x4*)(g + col), g1 = *(const f32x4*)(g + col + 4), b0 = *(const f32x4*)(bt + col), b1 = *(const f32x4*)(bt + col + 4);
.LBB0_667:
	s_cmp_lt_i32 s44, 8
	s_cselect_b64 s[6:7], -1, 0
	s_and_b64 s[6:7], s[6:7], s[4:5]
	s_and_b64 s[4:5], s[6:7], s[10:11]
	s_andn2_b64 vcc, exec, s[4:5]
	s_cbranch_vccnz .LBB0_672
	s_ashr_i32 s39, s38, 31
	s_lshl_b64 s[4:5], s[38:39], 12
	s_add_u32 s12, s8, s4
	s_addc_u32 s13, s9, s5
	global_load_dwordx4 v[28:31], v136, s[12:13]
	global_load_dwordx4 v[24:27], v136, s[12:13] offset:1024
	global_load_dwordx4 v[20:23], v136, s[12:13] offset:2048
	global_load_dwordx4 v[16:19], v136, s[12:13] offset:3072
	v_mbcnt_hi_u32_b32 v0, -1, v172
	v_and_b32_e32 v1, 64, v0
	v_add_u32_e32 v1, 64, v1
	v_xor_b32_e32 v2, 1, v0
	v_cmp_lt_i32_e32 vcc, v2, v1
	s_load_dwordx4 s[12:15], s[0:1], 0xb0
	v_mov_b32_e32 v137, 0
	v_cndmask_b32_e32 v2, v0, v2, vcc
	v_lshlrev_b32_e32 v53, 2, v2
	v_xor_b32_e32 v2, 2, v0
	v_cmp_lt_i32_e32 vcc, v2, v1
	v_mov_b32_e32 v139, v137
	s_waitcnt lgkmcnt(0)
	v_lshl_add_u64 v[32:33], s[12:13], 0, v[138:139]
	v_cndmask_b32_e32 v2, v0, v2, vcc
	v_lshlrev_b32_e32 v54, 2, v2
	v_xor_b32_e32 v2, 4, v0
	v_cmp_lt_i32_e32 vcc, v2, v1
	v_lshl_add_u64 v[34:35], s[14:15], 0, v[138:139]
	s_movk_i32 s3, 0x7fff
	v_cndmask_b32_e32 v2, v0, v2, vcc
	v_lshlrev_b32_e32 v55, 2, v2
	v_xor_b32_e32 v2, 8, v0
	v_cmp_lt_i32_e32 vcc, v2, v1
	s_mov_b32 s20, 0xffff0000
	v_mov_b32_e32 v59, 0x3727c5ac
	v_cndmask_b32_e32 v2, v0, v2, vcc
	v_lshlrev_b32_e32 v56, 2, v2
	v_xor_b32_e32 v2, 16, v0
	v_cmp_lt_i32_e32 vcc, v2, v1
	s_mov_b32 s21, 0xf800000
	v_mov_b32_e32 v60, 0x260
	v_cndmask_b32_e32 v2, v0, v2, vcc
	v_lshlrev_b32_e32 v57, 2, v2
	v_xor_b32_e32 v2, 32, v0
	v_cmp_lt_i32_e32 vcc, v2, v1
	v_mov_b32_e32 v1, v137
	s_mov_b32 s22, 0x25800000
	v_cndmask_b32_e32 v0, v0, v2, vcc
	v_lshlrev_b32_e32 v58, 2, v0
	v_or_b32_e32 v0, 0x1000, v138
	v_lshl_add_u64 v[36:37], s[12:13], 0, v[0:1]
	v_lshl_add_u64 v[38:39], s[14:15], 0, v[0:1]
	v_or_b32_e32 v0, 0x1800, v138
	v_lshl_add_u64 v[40:41], s[12:13], 0, v[0:1]
	s_add_u32 s12, s42, s4
	s_addc_u32 s13, s43, s5
	s_add_i32 s4, s38, s56
	s_ashr_i32 s57, s56, 31
	s_ashr_i32 s5, s4, 31
	v_lshl_add_u64 v[42:43], s[14:15], 0, v[0:1]
	s_lshl_b64 s[14:15], s[56:57], 12
	s_lshl_b64 s[4:5], s[4:5], 12
	s_add_u32 s16, s42, s4
	s_addc_u32 s17, s43, s5
	s_mov_b32 s23, s38
	global_load_dwordx4 v[176:179], v[32:33], off
	global_load_dwordx4 v[184:187], v[34:35], off
	global_load_dwordx4 v[180:183], v[32:33], off offset:16
	global_load_dwordx4 v[188:191], v[34:35], off offset:16
	global_load_dwordx4 v[192:195], v[32:33], off offset:2048
	global_load_dwordx4 v[200:203], v[34:35], off offset:2048
	global_load_dwordx4 v[196:199], v[32:33], off offset:2064
	global_load_dwordx4 v[204:207], v[34:35], off offset:2064
	global_load_dwordx4 v[208:211], v[36:37], off
	global_load_dwordx4 v[216:219], v[38:39], off
	global_load_dwordx4 v[212:215], v[36:37], off offset:16
	global_load_dwordx4 v[220:223], v[38:39], off offset:16
	global_load_dwordx4 v[224:227], v[40:41], off
	global_load_dwordx4 v[232:235], v[42:43], off
	global_load_dwordx4 v[228:231], v[40:41], off offset:16
	global_load_dwordx4 v[236:239], v[42:43], off offset:16
	s_mov_b32 s98, 0
	s_add_i32 s99, s38, s56
	s_cmpk_gt_i32 s99, 0x7fff
	s_cbranch_scc1 .Lln2_pre_done
	v_lshl_add_u64 v[124:125], s[16:17], 0, v[136:137]
	v_add_co_u32_e32 v124, vcc, 0x35800000, v124
	s_nop 1
	v_addc_co_u32_e32 v125, vcc, 0, v125, vcc
	global_load_dwordx4 v[4:7], v[124:125], off
	global_load_dwordx4 v[8:11], v[124:125], off offset:1024
	global_load_dwordx4 v[12:15], v[124:125], off offset:2048
	global_load_dwordx4 v[0:3], v[124:125], off offset:3072
	s_add_u32 s16, s16, s14
	s_addc_u32 s17, s17, s15

; __device__ __forceinline__ unsigned pk2(float lo, float hi) { return f2bf(lo) | (f2bf(hi) << 16); }
; __device__ __forceinline__ float bflo(unsigned w) { return __uint_as_float(w << 16); }
; __device__ __forceinline__ float bfhi(unsigned w) { return __uint_as_float(w & 0xffff0000u); }
; __device__ __forceinline__ void ln_rows(const bf16* Yb, const float* g, const float* bt, float* outf, bf16* outb, int gw, int NGW, int lane) {
;     u32x4 nx[4];
;     if (gw < M) { const u32x4* yr = (const u32x4*)(Yb + (size_t)gw * D) + lane;
; #pragma unroll
;         for (int j = 0; j < 4; ++j) nx[j] = yr[64 * j]; }
;     for (int row = gw; row < M; row += NGW) {
;         float v[4][8]; float s = 0.f;
; #pragma unroll
;         for (int j = 0; j < 4; ++j) { const u32x4 w = nx[j]; v[j][0] = bflo(w.x); v[j][1] = bfhi(w.x); v[j][2] = bflo(w.y); v[j][3] = bfhi(w.y); v[j][4] = bflo(w.z); v[j][5] = bfhi(w.z); v[j][6] = bflo(w.w); v[j][7] = bfhi(w.w);
;             s += ((v[j][0] + v[j][1]) + (v[j][2] + v[j][3])) + ((v[j][4] + v[j][5]) + (v[j][6] + v[j][7])); }
;         if (row + NGW < M) { const u32x4* yr = (const u32x4*)(Yb + (size_t)(row + NGW) * D) + lane;
; #pragma unroll
;             for (int j = 0; j < 4; ++j) nx[j] = yr[64 * j]; }
;         const float mean = wave_sum(s) * (1.f / D); float s2 = 0.f;
; #pragma unroll
;         for (int j = 0; j < 4; ++j)
; #pragma unroll
;             for (int i = 0; i < 8; ++i) { v[j][i] -= mean; s2 += v[j][i] * v[j][i]; }
;         const float rstd = 1.f / sqrtf(wave_sum(s2) * (1.f / D) + LN_EPS);
; #pragma unroll
;         for (int j = 0; j < 4; ++j) { const int col = 8 * (lane + 64 * j);
;             const f32x4 g0 = *(const f32x4*)(g + col), g1 = *(const f32x4*)(g + col + 4), b0 = *(const f32x4*)(bt + col), b1 = *(const f32x4*)(bt + col + 4);
;             const f32x4 o0 = (f32x4){v[j][0], v[j][1], v[j][2], v[j][3]} * rstd * g0 + b0, o1 = (f32x4){v[j][4], v[j][5], v[j][6], v[j][7]} * rstd * g1 + b1;
;             if (outf) { *(f32x4*)(outf + (size_t)row * D + col) = o0; *(f32x4*)(outf + (size_t)row * D + col + 4) = o1; }
;             if (outb) { u32x4 w; w.x = pk2(o0[0], o0[1]); w.y = pk2(o0[2], o0[3]); w.z = pk2(o1[0], o1[1]); w.w = pk2(o1[2], o1[3]); *(u32x4*)(outb + (size_t)row * D + col) = w; } }
.LBB0_805:
	s_cmp_lt_i32 s44, 10
	s_cselect_b64 s[4:5], -1, 0
	s_and_b64 s[2:3], s[4:5], s[2:3]
	s_and_b64 s[2:3], s[2:3], s[10:11]
	s_andn2_b64 vcc, exec, s[2:3]
	s_cbranch_vccnz .LBB0_812
	s_ashr_i32 s39, s38, 31
	s_lshl_b64 s[2:3], s[38:39], 12
	s_add_u32 s2, s8, s2
	s_addc_u32 s3, s9, s3
	global_load_dwordx4 v[28:31], v136, s[2:3]
	global_load_dwordx4 v[24:27], v136, s[2:3] offset:1024
	global_load_dwordx4 v[20:23], v136, s[2:3] offset:2048
	global_load_dwordx4 v[16:19], v136, s[2:3] offset:3072
	v_mbcnt_hi_u32_b32 v0, -1, v172
	v_and_b32_e32 v1, 64, v0
	v_add_u32_e32 v1, 64, v1
	v_xor_b32_e32 v2, 1, v0
	v_cmp_lt_i32_e32 vcc, v2, v1
	s_load_dwordx4 s[4:7], s[0:1], 0xd8
	s_cmp_lg_u64 s[40:41], 0
	v_cndmask_b32_e32 v2, v0, v2, vcc
	v_lshlrev_b32_e32 v64, 2, v2
	v_xor_b32_e32 v2, 2, v0
	v_cmp_lt_i32_e32 vcc, v2, v1
	v_mov_b32_e32 v137, 0
	s_cselect_b64 s[2:3], -1, 0
	v_cndmask_b32_e32 v2, v0, v2, vcc
	v_lshlrev_b32_e32 v65, 2, v2
	v_xor_b32_e32 v2, 4, v0
	v_cmp_lt_i32_e32 vcc, v2, v1
	s_lshl_b64 s[0:1], s[38:39], 13
	s_add_u32 s0, s40, s0
	v_cndmask_b32_e32 v2, v0, v2, vcc
	v_lshlrev_b32_e32 v66, 2, v2
	v_xor_b32_e32 v2, 8, v0
	v_cmp_lt_i32_e32 vcc, v2, v1
	v_mov_b32_e32 v139, v137
	s_addc_u32 s1, s41, s1
	v_cndmask_b32_e32 v2, v0, v2, vcc
	v_lshlrev_b32_e32 v67, 2, v2
	v_xor_b32_e32 v2, 16, v0
	v_cmp_lt_i32_e32 vcc, v2, v1
	s_ashr_i32 s57, s56, 31
	s_waitcnt lgkmcnt(0)
	v_lshl_add_u64 v[32:33], s[4:5], 0, v[138:139]
	v_cndmask_b32_e32 v2, v0, v2, vcc
	v_lshlrev_b32_e32 v68, 2, v2
	v_xor_b32_e32 v2, 32, v0
	v_cmp_lt_i32_e32 vcc, v2, v1
	v_mov_b32_e32 v1, v137
	v_lshl_add_u64 v[34:35], s[6:7], 0, v[138:139]
	v_cndmask_b32_e32 v0, v0, v2, vcc
	v_lshlrev_b32_e32 v69, 2, v0
	v_or_b32_e32 v0, 0x1000, v138
	v_lshl_add_u64 v[36:37], s[4:5], 0, v[0:1]
	v_lshl_add_u64 v[38:39], s[6:7], 0, v[0:1]
	v_or_b32_e32 v0, 0x1800, v138
	v_lshl_add_u64 v[40:41], s[4:5], 0, v[0:1]
	v_lshl_add_u64 v[42:43], s[6:7], 0, v[0:1]
	v_lshl_add_u64 v[0:1], s[0:1], 0, v[138:139]
	s_mov_b64 s[0:1], 0x1000
	v_lshl_add_u64 v[44:45], v[0:1], 0, s[0:1]
	s_add_i32 s0, s38, s56
	s_ashr_i32 s1, s0, 31
	s_lshl_b64 s[4:5], s[56:57], 13
	s_lshl_b64 s[0:1], s[0:1], 12
	s_add_u32 s0, s42, s0
	s_addc_u32 s1, s43, s1
	v_lshl_add_u64 v[0:1], s[0:1], 0, v[136:137]
	s_mov_b64 s[0:1], 0x35800000
	v_lshl_add_u64 v[46:47], v[0:1], 0, s[0:1]
	s_lshl_b64 s[6:7], s[56:57], 12
	v_mov_b32_e32 v70, 0x3727c5ac
	s_mov_b32 s10, 0xf800000
	v_mov_b32_e32 v71, 0x260
	global_load_dwordx4 v[176:179], v[32:33], off
	global_load_dwordx4 v[184:187], v[34:35], off
	global_load_dwordx4 v[180:183], v[32:33], off offset:16
	global_load_dwordx4 v[188:191], v[34:35], off offset:16
	global_load_dwordx4 v[192:195], v[32:33], off offset:2048
	global_load_dwordx4 v[200:203], v[34:35], off offset:2048
	global_load_dwordx4 v[196:199], v[32:33], off offset:2064
	global_load_dwordx4 v[204:207], v[34:35], off offset:2064
	global_load_dwordx4 v[208:211], v[36:37], off
	global_load_dwordx4 v[216:219], v[38:39], off
	global_load_dwordx4 v[212:215], v[36:37], off offset:16
	global_load_dwordx4 v[220:223], v[38:39], off offset:16
	global_load_dwordx4 v[224:227], v[40:41], off
	global_load_dwordx4 v[232:235], v[42:43], off
	global_load_dwordx4 v[228:231], v[40:41], off offset:16
	global_load_dwordx4 v[236:239], v[42:43], off offset:16
	s_mov_b32 s98, 0
	s_add_i32 s99, s38, s56
	s_cmpk_gt_i32 s99, 0x7fff
	s_cbranch_scc1 .Lln3_pre_done
	global_load_dwordx4 v[0:3], v[46:47], off
	global_load_dwordx4 v[4:7], v[46:47], off offset:1024
	global_load_dwordx4 v[8:11], v[46:47], off offset:2048
	global_load_dwordx4 v[12:15], v[46:47], off offset:3072
	v_lshl_add_u64 v[46:47], v[46:47], 0, s[6:7]

; __device__ __forceinline__ float bflo(unsigned w) { return __uint_as_float(w << 16); }
; __device__ __forceinline__ float bfhi(unsigned w) { return __uint_as_float(w & 0xffff0000u); }
; __device__ __forceinline__ void ln_rows(const bf16* Yb, const float* g, const float* bt, float* outf, bf16* outb, int gw, int NGW, int lane) {
;     ...
;     for (int row = gw; row < M; row += NGW) {
;         float v[4][8]; float s = 0.f;
; #pragma unroll
;         for (int j = 0; j < 4; ++j) { const u32x4 w = nx[j]; v[j][0] = bflo(w.x); v[j][1] = bfhi(w.x); v[j][2] = bflo(w.y); v[j][3] = bfhi(w.y); v[j][4] = bflo(w.z); v[j][5] = bfhi(w.z); v[j][6] = bflo(w.w); v[j][7] = bfhi(w.w);
;             s += ((v[j][0] + v[j][1]) + (v[j][2] + v[j][3])) + ((v[j][4] + v[j][5]) + (v[j][6] + v[j][7])); }
;         if (row + NGW < M) { const u32x4* yr = (const u32x4*)(Yb + (size_t)(row + NGW) * D) + lane;
; #pragma unroll
;             for (int j = 0; j < 4; ++j) nx[j] = yr[64 * j]; }
.LBB0_807:
	v_lshl_add_u64 v[44:45], v[44:45], 0, s[4:5]
	v_lshl_add_u64 v[46:47], v[46:47], 0, s[6:7]
	s_andn2_b64 vcc, exec, s[8:9]
	s_waitcnt vmcnt(16)
	s_cmp_eq_u32 s98, 0
	s_cbranch_scc1 .Lln3_cpN2
	v_mov_b32_e32 v28, v0
	v_mov_b32_e32 v29, v1
	v_mov_b32_e32 v30, v2
	v_mov_b32_e32 v31, v3
	v_mov_b32_e32 v24, v4
	v_mov_b32_e32 v25, v5
	v_mov_b32_e32 v26, v6
	v_mov_b32_e32 v27, v7
	v_mov_b32_e32 v20, v8
	v_mov_b32_e32 v21, v9
	v_mov_b32_e32 v22, v10
	v_mov_b32_e32 v23, v11
	v_mov_b32_e32 v16, v12
	v_mov_b32_e32 v17, v13
	v_mov_b32_e32 v18, v14
	v_mov_b32_e32 v19, v15
	s_branch .Lln3_cpdone

; __device__ __forceinline__ float bflo(unsigned w) { return __uint_as_float(w << 16); }
; __device__ __forceinline__ float bfhi(unsigned w) { return __uint_as_float(w & 0xffff0000u); }
; __device__ __forceinline__ void ln_rows(const bf16* Yb, const float* g, const float* bt, float* outf, bf16* outb, int gw, int NGW, int lane) {
;     ...
;     for (int row = gw; row < M; row += NGW) {
;         float v[4][8]; float s = 0.f;
; #pragma unroll
;         for (int j = 0; j < 4; ++j) { const u32x4 w = nx[j]; v[j][0] = bflo(w.x); v[j][1] = bfhi(w.x); v[j][2] = bflo(w.y); v[j][3] = bfhi(w.y); v[j][4] = bflo(w.z); v[j][5] = bfhi(w.z); v[j][6] = bflo(w.w); v[j][7] = bfhi(w.w);
;             s += ((v[j][0] + v[j][1]) + (v[j][2] + v[j][3])) + ((v[j][4] + v[j][5]) + (v[j][6] + v[j][7])); }
;         if (row + NGW < M) { const u32x4* yr = (const u32x4*)(Yb + (size_t)(row + NGW) * D) + lane;
; #pragma unroll
;             for (int j = 0; j < 4; ++j) nx[j] = yr[64 * j]; }
.Lln3_cpdone:
	s_cbranch_vccz .LBB0_812
.LBB0_808:
	s_add_i32 s38, s38, s56
	s_cmpk_gt_i32 s38, 0x7fff
	s_cselect_b64 s[8:9], -1, 0
	s_xor_b32 s98, s98, 1
	s_add_i32 s99, s38, s56
	s_cmpk_gt_i32 s99, 0x7fff
	s_cbranch_scc1 .LBB0_810
	s_cmp_eq_u32 s98, 0
	s_cbranch_scc1 .Lln3_pfN1
	global_load_dwordx4 v[108:111], v[46:47], off
	global_load_dwordx4 v[112:115], v[46:47], off offset:1024
	global_load_dwordx4 v[116:119], v[46:47], off offset:2048
	global_load_dwordx4 v[120:123], v[46:47], off offset:3072
	s_branch .LBB0_810
.Lln3_pfN1:
	global_load_dwordx4 v[0:3], v[46:47], off
	global_load_dwordx4 v[4:7], v[46:47], off offset:1024
	global_load_dwordx4 v[8:11], v[46:47], off offset:2048
	global_load_dwordx4 v[12:15], v[46:47], off offset:3072

; #define LAS __attribute__((address_space(3)))
; __global__ void __launch_bounds__(NWAVES * 64, 2) hymba_fwd(Args args) {
;     extern __shared__ __attribute__((aligned(16))) unsigned char lds_raw[];
;     LAS unsigned char* lds = (LAS unsigned char*)lds_raw;
;     cg::grid_group grid = cg::this_grid();
;     const int tid = threadIdx.x, lane = tid & 63, wave = __builtin_amdgcn_readfirstlane(tid >> 6);
	.amdhsa_kernel _Z9hymba_fwd4Args
		.amdhsa_group_segment_fixed_size 0
		.amdhsa_private_segment_fixed_size 0
		.amdhsa_kernarg_size 512
		.amdhsa_user_sgpr_count 2
		.amdhsa_user_sgpr_dispatch_ptr 0
		.amdhsa_user_sgpr_queue_ptr 0
		.amdhsa_user_sgpr_kernarg_segment_ptr 1
		.amdhsa_user_sgpr_dispatch_id 0
		.amdhsa_user_sgpr_kernarg_preload_length 0
		.amdhsa_user_sgpr_kernarg_preload_offset 0
		.amdhsa_user_sgpr_private_segment_size 0
		.amdhsa_uses_dynamic_stack 0
		.amdhsa_enable_private_segment 0
		.amdhsa_system_sgpr_workgroup_id_x 1
		.amdhsa_system_sgpr_workgroup_id_y 0
		.amdhsa_system_sgpr_workgroup_id_z 0
		.amdhsa_system_sgpr_workgroup_info 0
		.amdhsa_system_vgpr_workitem_id 2
		.amdhsa_next_free_vgpr 255
		.amdhsa_next_free_sgpr 100
		.amdhsa_accum_offset 256
		.amdhsa_reserve_vcc 1
		.amdhsa_float_round_mode_32 0
		.amdhsa_float_round_mode_16_64 0
		.amdhsa_float_denorm_mode_32 3
		.amdhsa_float_denorm_mode_16_64 3
		.amdhsa_dx10_clamp 1
		.amdhsa_ieee_mode 1
		.amdhsa_fp16_overflow 0
		.amdhsa_tg_split 0
		.amdhsa_exception_fp_ieee_invalid_op 0
		.amdhsa_exception_fp_denorm_src 0
		.amdhsa_exception_fp_ieee_div_zero 0
		.amdhsa_exception_fp_ieee_overflow 0
		.amdhsa_exception_fp_ieee_underflow 0
		.amdhsa_exception_fp_ieee_inexact 0
		.amdhsa_exception_int_div_zero 0
	.end_amdhsa_kernel

; #define LAS __attribute__((address_space(3)))
; __global__ void __launch_bounds__(NWAVES * 64, 2) hymba_fwd(Args args) {
;     extern __shared__ __attribute__((aligned(16))) unsigned char lds_raw[];
;     LAS unsigned char* lds = (LAS unsigned char*)lds_raw;
;     cg::grid_group grid = cg::this_grid();
;     const int tid = threadIdx.x, lane = tid & 63, wave = __builtin_amdgcn_readfirstlane(tid >> 6);
amdhsa.kernels:
  - .agpr_count:     0
    .args:
      - .offset:         0
        .size:           256
        .value_kind:     by_value
      - .offset:         256
        .size:           4
        .value_kind:     hidden_block_count_x
      - .offset:         260
        .size:           4
        .value_kind:     hidden_block_count_y
      - .offset:         264
        .size:           4
        .value_kind:     hidden_block_count_z
      - .offset:         268
        .size:           2
        .value_kind:     hidden_group_size_x
      - .offset:         270
        .size:           2
        .value_kind:     hidden_group_size_y
      - .offset:         272
        .size:           2
        .value_kind:     hidden_group_size_z
      - .offset:         274
        .size:           2
        .value_kind:     hidden_remainder_x
      - .offset:         276
        .size:           2
        .value_kind:     hidden_remainder_y
      - .offset:         278
        .size:           2
        .value_kind:     hidden_remainder_z
      - .offset:         296
        .size:           8
        .value_kind:     hidden_global_offset_x
      - .offset:         304
        .size:           8
        .value_kind:     hidden_global_offset_y
      - .offset:         312
        .size:           8
        .value_kind:     hidden_global_offset_z
      - .offset:         320
        .size:           2
        .value_kind:     hidden_grid_dims
      - .offset:         344
        .size:           8
        .value_kind:     hidden_multigrid_sync_arg
      - .offset:         376
        .size:           4
        .value_kind:     hidden_dynamic_lds_size
    .group_segment_fixed_size: 0
    .kernarg_segment_align: 8
    .kernarg_segment_size: 512
    .language:       OpenCL C
    .language_version:
      - 2
      - 0
    .max_flat_workgroup_size: 512
    .name:           _Z9hymba_fwd4Args
    .private_segment_fixed_size: 0
    .sgpr_count:     106
    .sgpr_spill_count: 6
    .symbol:         _Z9hymba_fwd4Args.kd
    .uniform_work_group_size: 1
    .uses_dynamic_stack: false
    .vgpr_count:     255
    .vgpr_spill_count: 0
    .wavefront_size: 64
